# GLA chain loop: global addresses as workspace base + 32-bit lane offset + constant in an SGPR pair (scalar adds) instead of a VALU 64-bit add pair per access
# speedup vs baseline: 1.0059x; 1.0059x over previous
.LBB0_1085:
	s_or_b64 exec, exec, s[8:9]
	s_waitcnt vmcnt(18)
	v_lshlrev_b32_e32 v112, 16, v100
	v_and_b32_e32 v113, 0xffff0000, v100
	v_mul_f32_e32 v100, 0xbfb8aa3b, v112
	v_exp_f32_e32 v100, v100
	v_pk_mul_f32 v[110:111], v[20:21], v[110:111]
	v_pk_mul_f32 v[108:109], v[22:23], v[108:109]
	v_pk_mul_f32 v[106:107], v[16:17], v[106:107]
	v_add_f32_e32 v100, 1.0, v100
	v_rcp_f32_e32 v114, v100
	v_mul_f32_e32 v100, 0xbfb8aa3b, v113
	v_exp_f32_e32 v100, v100
	v_pk_mul_f32 v[104:105], v[18:19], v[104:105]
	s_mov_b32 s8, 0x12880000
	s_mov_b64 s[38:39], 0xc0000
	v_add_f32_e32 v100, 1.0, v100
	v_rcp_f32_e32 v115, v100
	s_add_i32 s22, s22, 3
	v_lshl_add_u64 v[126:127], v[126:127], 0, s[38:39]
	v_add_u32_e32 v161, 0x600, v161
	v_pk_mul_f32 v[112:113], v[114:115], v[112:113]
	v_lshl_add_u64 v[122:123], v[122:123], 0, s[38:39]
	v_pk_mul_f32 v[110:111], v[112:113], v[110:111]
	s_cmp_gt_u32 s31, 28
	v_cvt_pk_bf16_f32 v100, v110, v111
	v_lshlrev_b32_e32 v110, 16, v101
	v_and_b32_e32 v111, 0xffff0000, v101
	v_mul_f32_e32 v101, 0xbfb8aa3b, v110
	v_exp_f32_e32 v101, v101
	s_nop 0
	v_add_f32_e32 v101, 1.0, v101
	v_rcp_f32_e32 v112, v101
	v_mul_f32_e32 v101, 0xbfb8aa3b, v111
	v_exp_f32_e32 v101, v101
	s_nop 0
	v_add_f32_e32 v101, 1.0, v101
	v_rcp_f32_e32 v113, v101
	s_nop 0
	v_pk_mul_f32 v[110:111], v[112:113], v[110:111]
	s_nop 0
	v_pk_mul_f32 v[108:109], v[110:111], v[108:109]
	s_nop 0
	v_cvt_pk_bf16_f32 v101, v108, v109
	v_lshlrev_b32_e32 v108, 16, v102
	v_and_b32_e32 v109, 0xffff0000, v102
	v_mul_f32_e32 v102, 0xbfb8aa3b, v108
	v_exp_f32_e32 v102, v102
	s_nop 0
	v_add_f32_e32 v102, 1.0, v102
	v_rcp_f32_e32 v110, v102
	v_mul_f32_e32 v102, 0xbfb8aa3b, v109
	v_exp_f32_e32 v102, v102
	s_nop 0
	v_add_f32_e32 v102, 1.0, v102
	v_rcp_f32_e32 v111, v102
	s_nop 0
	v_pk_mul_f32 v[108:109], v[110:111], v[108:109]
	s_nop 0
	v_pk_mul_f32 v[106:107], v[108:109], v[106:107]
	s_nop 0
	v_cvt_pk_bf16_f32 v102, v106, v107
	v_lshlrev_b32_e32 v106, 16, v103
	v_and_b32_e32 v107, 0xffff0000, v103
	v_mul_f32_e32 v103, 0xbfb8aa3b, v106
	v_exp_f32_e32 v103, v103
	s_nop 0
	v_add_f32_e32 v103, 1.0, v103
	v_rcp_f32_e32 v108, v103
	v_mul_f32_e32 v103, 0xbfb8aa3b, v107
	v_exp_f32_e32 v103, v103
	s_nop 0
	v_add_f32_e32 v103, 1.0, v103
	v_rcp_f32_e32 v109, v103
	s_nop 0
	v_pk_mul_f32 v[106:107], v[108:109], v[106:107]
	s_nop 0
	v_pk_mul_f32 v[104:105], v[106:107], v[104:105]
	s_nop 0
	v_cvt_pk_bf16_f32 v103, v104, v105
	s_mov_b64 s[8:9], 0xc000
	s_nop 0
	s_add_u32 s44, s6, 0x127c0000
	s_addc_u32 s45, s7, 0
	global_store_dwordx4 v122, v[100:103], s[44:45]
	s_waitcnt lgkmcnt(0)
	s_barrier
	v_lshl_add_u64 v[124:125], v[124:125], 0, s[8:9]
	v_lshl_add_u64 v[128:129], v[128:129], 0, s[8:9]
	v_lshl_add_u64 v[130:131], v[130:131], 0, s[8:9]
	s_mov_b64 s[8:9], 0x3000
	v_lshl_add_u64 v[120:121], v[120:121], 0, s[8:9]
	s_cmp_gt_u32 s31, 28
	s_cbranch_scc1 .LBB0_1092
.LBB0_1086:
	s_and_b32 s40, s22, 1
	s_mul_i32 s8, s40, 0x6c00
	v_readlane_b32 s38, v254, 54
	s_add_i32 s41, s38, s8
	v_add_u32_e32 v100, s41, v146
	v_lshl_add_u64 v[132:133], s[6:7], 0, v[124:125]
	ds_write_b128 v100, v[24:27]
	ds_write_b128 v100, v[28:31] offset:9216
	ds_write_b128 v100, v[32:35] offset:18432
	v_lshl_add_u64 v[136:137], s[6:7], 0, v[128:129]
	s_nop 0
	s_mov_b32 s8, 0xb40c000
	v_lshl_add_u64 v[138:139], s[6:7], 0, v[126:127]
	s_nop 0
	v_lshl_add_u64 v[140:141], s[6:7], 0, v[130:131]
	s_add_u32 s44, s6, 0x0
	s_addc_u32 s45, s7, 0
	global_load_dwordx4 v[24:27], v124, s[44:45]
	s_nop 0
	s_add_u32 s44, s6, 0x2000
	s_addc_u32 s45, s7, 0
	global_load_dwordx4 v[28:31], v124, s[44:45]
	s_nop 0
	s_add_u32 s44, s6, 0xb40c000
	s_addc_u32 s45, s7, 0
	global_load_dwordx4 v[116:119], v128, s[44:45]
	global_load_dwordx4 v[112:115], v128, s[44:45] offset:64
	global_load_dwordx4 v[108:111], v128, s[44:45] offset:128
	global_load_dwordx4 v[104:107], v128, s[44:45] offset:192
	s_nop 0
	s_add_u32 s44, s6, 0x0
	s_addc_u32 s45, s7, 0
	global_load_dwordx4 v[32:35], v126, s[44:45]
	s_add_u32 s44, s6, 0x0
	s_addc_u32 s45, s7, 0
	global_load_dwordx4 v[100:103], v130, s[44:45]
	s_add_i32 s31, s22, -1
	s_and_b32 s8, s31, 1
	s_mul_i32 s9, s8, 0x6c00
	s_add_i32 s38, s38, s9
	v_mov_b32_e32 v134, s38
	ds_read_b128 v[162:165], v161
	ds_read_b128 v[166:169], v161 offset:32
	ds_read_b128 v[170:173], v161 offset:64
	ds_read_b128 v[174:177], v161 offset:96
	s_waitcnt lgkmcnt(3)
	v_pk_mul_f32 v[2:3], v[2:3], v[164:165]
	v_add_u32_e32 v135, v134, v147
	v_add_u32_e32 v134, v134, v145
	ds_read_b128 v[178:181], v135
	ds_read_b128 v[182:185], v134 offset:18432
	s_waitcnt lgkmcnt(2)
	v_pk_mul_f32 v[14:15], v[14:15], v[176:177]
	v_pk_mul_f32 v[10:11], v[10:11], v[172:173]
	v_pk_mul_f32 v[6:7], v[6:7], v[168:169]
	v_pk_mul_f32 v[12:13], v[12:13], v[174:175]
	v_pk_mul_f32 v[8:9], v[8:9], v[170:171]
	v_pk_mul_f32 v[4:5], v[4:5], v[166:167]
	v_pk_mul_f32 v[0:1], v[0:1], v[162:163]
	ds_read_b128 v[162:165], v135 offset:32
	ds_read_b128 v[166:169], v134 offset:18464
	s_waitcnt lgkmcnt(2)
	v_mfma_f32_32x32x16_bf16 v[0:15], v[178:181], v[182:185], v[0:15]
	s_mul_i32 s9, s8, 0x4400
	s_add_i32 s42, s9, 0
	s_xor_b32 s39, s8, 1
	s_mul_i32 s9, s39, 0x4400
	s_waitcnt lgkmcnt(0)
	v_mfma_f32_32x32x16_bf16 v[0:15], v[162:165], v[166:169], v[0:15]
	ds_read_b128 v[162:165], v135 offset:64
	ds_read_b128 v[166:169], v134 offset:18496
	ds_read_b128 v[170:173], v135 offset:96
	ds_read_b128 v[174:177], v134 offset:18528
	v_add_u32_e32 v134, s42, v150
	s_waitcnt lgkmcnt(2)
	v_mfma_f32_32x32x16_bf16 v[0:15], v[162:165], v[166:169], v[0:15]
	v_add_u32_e32 v162, 0x6000, v134
	v_mov_b32_e32 v158, v162
	s_waitcnt lgkmcnt(0)
	v_mfma_f32_32x32x16_bf16 v[0:15], v[170:173], v[174:177], v[0:15]
	s_nop 11
	v_cvt_pk_bf16_f32 v134, v0, v1
	v_cvt_pk_bf16_f32 v135, v2, v3
	v_cvt_pk_bf16_f32 v142, v4, v5
	v_cvt_pk_bf16_f32 v143, v6, v7
	ds_write2_b64 v158, v[134:135], v[142:143] offset1:2
	v_cvt_pk_bf16_f32 v134, v8, v9
	v_cvt_pk_bf16_f32 v135, v10, v11
	v_cvt_pk_bf16_f32 v142, v12, v13
	v_cvt_pk_bf16_f32 v143, v14, v15
	ds_write2_b64 v158, v[134:135], v[142:143] offset0:4 offset1:6
	v_add_u32_e32 v134, s9, v152
	v_add_u32_e32 v164, 0x6000, v134
	v_mov_b32_e32 v134, v164
	ds_read_b128 v[166:169], v134
	ds_read_b128 v[170:173], v134 offset:64
	ds_read_b128 v[174:177], v134 offset:4352
	ds_read_b128 v[178:181], v134 offset:4416
	ds_read_b128 v[182:185], v134 offset:128
	ds_read_b128 v[186:189], v134 offset:192
	ds_read_b128 v[190:193], v134 offset:4480
	ds_read_b128 v[194:197], v134 offset:4544
	v_lshl_add_u64 v[134:135], s[6:7], 0, v[120:121]
	s_waitcnt vmcnt(20) lgkmcnt(7)
	v_mfma_f32_16x16x32_bf16 v[166:169], v[80:83], v[166:169], 0
	s_mul_i32 s9, s39, 0x4100
	v_add_u32_e32 v142, s9, v157
	v_add_u32_e32 v163, 0xe800, v142
	s_waitcnt lgkmcnt(5)
	v_mfma_f32_16x16x32_bf16 v[80:83], v[80:83], v[174:177], 0
	v_mov_b32_e32 v142, v163
	s_mulk_i32 s8, 0xfd00
	s_waitcnt vmcnt(19)
	v_mfma_f32_16x16x32_bf16 v[166:169], v[76:79], v[170:173], v[166:169]
	s_add_i32 s43, s42, s8
	v_lshlrev_b32_e32 v158, 2, v144
	s_mov_b32 s8, 0xe800
	s_waitcnt lgkmcnt(4)
	v_mfma_f32_16x16x32_bf16 v[76:79], v[76:79], v[178:181], v[80:83]
	s_waitcnt vmcnt(18) lgkmcnt(3)
	v_mfma_f32_16x16x32_bf16 v[80:83], v[72:75], v[182:185], v[166:169]
	s_waitcnt lgkmcnt(1)
	v_mfma_f32_16x16x32_bf16 v[72:75], v[72:75], v[190:193], v[76:79]
	s_waitcnt vmcnt(17)
	v_mfma_f32_16x16x32_bf16 v[80:83], v[68:71], v[186:189], v[80:83]
	s_waitcnt lgkmcnt(0)
	v_mfma_f32_16x16x32_bf16 v[68:71], v[68:71], v[194:197], v[72:75]
	s_nop 5
	v_mul_f32_e32 v80, 0x3db504f3, v80
	s_nop 0
	v_mul_f32_e32 v68, 0x3db504f3, v68
	v_mul_f32_e32 v76, 0x3db504f3, v81
	ds_write2_b32 v142, v80, v68 offset1:16
	v_mul_f32_e32 v68, 0x3db504f3, v69
	v_mul_f32_e32 v77, 0x3db504f3, v82
	ds_write2_b32 v142, v76, v68 offset0:65 offset1:81
	v_mul_f32_e32 v68, 0x3db504f3, v70
	v_mul_f32_e32 v78, 0x3db504f3, v83
	ds_write2_b32 v142, v77, v68 offset0:130 offset1:146
	v_mul_f32_e32 v68, 0x3db504f3, v71
	ds_write2_b32 v142, v78, v68 offset0:195 offset1:211
	v_lshl_add_u32 v68, v159, 2, s43
	v_add3_u32 v165, v68, v158, s8
	v_mov_b32_e32 v68, v165
	ds_read2_b32 v[74:75], v68 offset1:1
	ds_read2_b32 v[72:73], v68 offset0:2 offset1:3
	ds_read2_b32 v[70:71], v68 offset0:4 offset1:5
	ds_read2_b32 v[68:69], v68 offset0:6 offset1:7
	s_waitcnt lgkmcnt(3)
	v_pk_mul_f32 v[76:77], v[74:75], v[74:75]
	s_waitcnt lgkmcnt(2)
	v_pk_mul_f32 v[78:79], v[72:73], v[72:73]
	v_add_f32_e32 v76, v76, v77
	v_add_f32_e32 v76, v76, v78
	s_waitcnt lgkmcnt(1)
	v_pk_mul_f32 v[80:81], v[70:71], v[70:71]
	v_add_f32_e32 v76, v76, v79
	v_add_f32_e32 v76, v76, v80
	s_waitcnt lgkmcnt(0)
	v_pk_mul_f32 v[82:83], v[68:69], v[68:69]
	v_add_f32_e32 v76, v76, v81
	v_add_f32_e32 v76, v76, v82
	v_add_f32_e32 v76, v76, v83
	s_nop 1
	v_add_f32_dpp v76, v76, v76 quad_perm:[1,0,3,2] row_mask:0xf bank_mask:0xf bound_ctrl:1
	s_nop 1
	v_add_f32_dpp v76, v76, v76 quad_perm:[2,3,0,1] row_mask:0xf bank_mask:0xf bound_ctrl:1
	s_nop 1
	v_mov_b32_dpp v77, v76 row_half_mirror row_mask:0xf bank_mask:0xf bound_ctrl:1
	s_and_saveexec_b64 s[8:9], s[4:5]
	s_cbranch_execz .LBB0_1088
	v_add_f32_e32 v78, v76, v77
	s_nop 1
	s_add_u32 s44, s6, 0x1a900000
	s_addc_u32 s45, s7, 0
	global_store_dword v120, v78, s[44:45]
.LBB0_1088:
	s_or_b64 exec, exec, s[8:9]
	s_waitcnt vmcnt(16)
	v_lshlrev_b32_e32 v76, 16, v40
	v_and_b32_e32 v77, 0xffff0000, v40
	v_mul_f32_e32 v40, 0xbfb8aa3b, v76
	v_exp_f32_e32 v40, v40
	v_pk_mul_f32 v[74:75], v[20:21], v[74:75]
	v_pk_mul_f32 v[72:73], v[22:23], v[72:73]
	v_pk_mul_f32 v[70:71], v[16:17], v[70:71]
	v_add_f32_e32 v40, 1.0, v40
	v_rcp_f32_e32 v78, v40
	v_mul_f32_e32 v40, 0xbfb8aa3b, v77
	v_exp_f32_e32 v40, v40
	s_mov_b64 s[8:9], 0x2000
	v_pk_mul_f32 v[68:69], v[18:19], v[68:69]
	v_lshl_add_u64 v[142:143], v[132:133], 0, s[8:9]
	v_add_f32_e32 v40, 1.0, v40
	v_rcp_f32_e32 v79, v40
	v_lshl_add_u64 v[132:133], s[6:7], 0, v[122:123]
	s_mov_b32 s8, 0x12800000
	s_bitcmp1_b32 s31, 0
	v_pk_mul_f32 v[76:77], v[78:79], v[76:77]
	s_nop 0
	v_pk_mul_f32 v[74:75], v[76:77], v[74:75]
	s_nop 0
	v_cvt_pk_bf16_f32 v40, v74, v75
	v_lshlrev_b32_e32 v74, 16, v41
	v_and_b32_e32 v75, 0xffff0000, v41
	v_mul_f32_e32 v41, 0xbfb8aa3b, v74
	v_exp_f32_e32 v41, v41
	s_nop 0
	v_add_f32_e32 v41, 1.0, v41
	v_rcp_f32_e32 v76, v41
	v_mul_f32_e32 v41, 0xbfb8aa3b, v75
	v_exp_f32_e32 v41, v41
	s_nop 0
	v_add_f32_e32 v41, 1.0, v41
	v_rcp_f32_e32 v77, v41
	s_nop 0
	v_pk_mul_f32 v[74:75], v[76:77], v[74:75]
	s_nop 0
	v_pk_mul_f32 v[72:73], v[74:75], v[72:73]
	s_nop 0
	v_cvt_pk_bf16_f32 v41, v72, v73
	v_lshlrev_b32_e32 v72, 16, v42
	v_and_b32_e32 v73, 0xffff0000, v42
	v_mul_f32_e32 v42, 0xbfb8aa3b, v72
	v_exp_f32_e32 v42, v42
	s_nop 0
	v_add_f32_e32 v42, 1.0, v42
	v_rcp_f32_e32 v74, v42
	v_mul_f32_e32 v42, 0xbfb8aa3b, v73
	v_exp_f32_e32 v42, v42
	s_nop 0
	v_add_f32_e32 v42, 1.0, v42
	v_rcp_f32_e32 v75, v42
	s_nop 0
	v_pk_mul_f32 v[72:73], v[74:75], v[72:73]
	s_nop 0
	v_pk_mul_f32 v[70:71], v[72:73], v[70:71]
	s_nop 0
	v_cvt_pk_bf16_f32 v42, v70, v71
	v_lshlrev_b32_e32 v70, 16, v43
	v_and_b32_e32 v71, 0xffff0000, v43
	v_mul_f32_e32 v43, 0xbfb8aa3b, v70
	v_exp_f32_e32 v43, v43
	s_nop 0
	v_add_f32_e32 v43, 1.0, v43
	v_rcp_f32_e32 v72, v43
	v_mul_f32_e32 v43, 0xbfb8aa3b, v71
	v_exp_f32_e32 v43, v43
	s_nop 0
	v_add_f32_e32 v43, 1.0, v43
	v_rcp_f32_e32 v73, v43
	s_nop 0
	v_pk_mul_f32 v[70:71], v[72:73], v[70:71]
	s_nop 0
	v_pk_mul_f32 v[68:69], v[70:71], v[68:69]
	s_nop 0
	v_cvt_pk_bf16_f32 v43, v68, v69
	s_cselect_b32 s8, 0x6c00, 0
	s_nop 0
	s_add_u32 s44, s6, 0x12800000
	s_addc_u32 s45, s7, 0
	global_store_dwordx4 v122, v[40:43], s[44:45]
	s_waitcnt lgkmcnt(0)
	s_barrier
	s_nop 0
	v_add_u32_e32 v40, s8, v148
	ds_write_b128 v40, v[44:47]
	ds_write_b128 v40, v[48:51] offset:9216
	ds_write_b128 v40, v[52:55] offset:18432
	s_mov_b32 s8, 0x40000
	s_nop 0
	s_add_u32 s44, s6, 0x4000
	s_addc_u32 s45, s7, 0
	global_load_dwordx4 v[44:47], v124, s[44:45]
	s_nop 1
	s_add_u32 s44, s6, 0x6000
	s_addc_u32 s45, s7, 0
	global_load_dwordx4 v[48:51], v124, s[44:45]
	s_mov_b32 s8, 0xb410000
	s_nop 0
	s_add_u32 s44, s6, 0x40000
	s_addc_u32 s45, s7, 0
	global_load_dwordx4 v[52:55], v126, s[44:45]
	s_mul_i32 s8, s40, 0x4400
	s_nop 0
	s_add_u32 s44, s6, 0xb410000
	s_addc_u32 s45, s7, 0
	global_load_dwordx4 v[80:83], v128, s[44:45]
	global_load_dwordx4 v[76:79], v128, s[44:45] offset:64
	global_load_dwordx4 v[72:75], v128, s[44:45] offset:128
	global_load_dwordx4 v[68:71], v128, s[44:45] offset:192
	s_nop 1
	s_add_u32 s44, s6, 0x4000
	s_addc_u32 s45, s7, 0
	global_load_dwordx4 v[40:43], v130, s[44:45]
	ds_read_b128 v[166:169], v161 offset:512
	ds_read_b128 v[170:173], v161 offset:544
	ds_read_b128 v[174:177], v161 offset:576
	ds_read_b128 v[178:181], v161 offset:608
	s_waitcnt lgkmcnt(3)
	v_pk_mul_f32 v[0:1], v[0:1], v[166:167]
	v_mov_b32_e32 v166, s41
	s_waitcnt lgkmcnt(1)
	v_pk_mul_f32 v[10:11], v[10:11], v[176:177]
	s_waitcnt lgkmcnt(0)
	v_pk_mul_f32 v[14:15], v[14:15], v[180:181]
	v_pk_mul_f32 v[6:7], v[6:7], v[172:173]
	v_pk_mul_f32 v[2:3], v[2:3], v[168:169]
	v_pk_mul_f32 v[12:13], v[12:13], v[178:179]
	v_pk_mul_f32 v[8:9], v[8:9], v[174:175]
	v_pk_mul_f32 v[4:5], v[4:5], v[170:171]
	s_nop 0
	v_add_u32_e32 v190, v166, v147
	v_add_u32_e32 v194, v166, v145
	ds_read_b128 v[166:169], v190
	ds_read_b128 v[170:173], v190 offset:32
	ds_read_b128 v[174:177], v194 offset:18432
	ds_read_b128 v[178:181], v194 offset:18464
	ds_read_b128 v[182:185], v190 offset:64
	ds_read_b128 v[186:189], v194 offset:18496
	ds_read_b128 v[190:193], v190 offset:96
	ds_read_b128 v[194:197], v194 offset:18528
	s_waitcnt lgkmcnt(5)
	v_mfma_f32_32x32x16_bf16 v[0:15], v[166:169], v[174:177], v[0:15]
	v_add_u32_e32 v166, s8, v151
	s_waitcnt lgkmcnt(4)
	v_mfma_f32_32x32x16_bf16 v[0:15], v[170:173], v[178:181], v[0:15]
	v_add_u32_e32 v170, 0x6000, v166
	s_waitcnt lgkmcnt(2)
	v_mfma_f32_32x32x16_bf16 v[0:15], v[182:185], v[186:189], v[0:15]
	s_waitcnt lgkmcnt(0)
	v_mfma_f32_32x32x16_bf16 v[0:15], v[190:193], v[194:197], v[0:15]
	s_nop 11
	v_cvt_pk_bf16_f32 v166, v0, v1
	v_cvt_pk_bf16_f32 v167, v2, v3
	v_cvt_pk_bf16_f32 v168, v4, v5
	v_cvt_pk_bf16_f32 v169, v6, v7
	ds_write2_b64 v170, v[166:167], v[168:169] offset1:2
	v_cvt_pk_bf16_f32 v166, v8, v9
	v_cvt_pk_bf16_f32 v167, v10, v11
	v_cvt_pk_bf16_f32 v168, v12, v13
	v_cvt_pk_bf16_f32 v169, v14, v15
	ds_write2_b64 v170, v[166:167], v[168:169] offset0:4 offset1:6
	v_add_u32_e32 v166, s42, v155
	v_add_u32_e32 v194, 0x6000, v166
	ds_read_b128 v[166:169], v194
	ds_read_b128 v[170:173], v194 offset:4352
	ds_read_b128 v[174:177], v194 offset:64
	ds_read_b128 v[178:181], v194 offset:4416
	ds_read_b128 v[182:185], v194 offset:128
	ds_read_b128 v[186:189], v194 offset:4480
	ds_read_b128 v[190:193], v194 offset:192
	ds_read_b128 v[194:197], v194 offset:4544
	s_waitcnt vmcnt(21) lgkmcnt(7)
	v_mfma_f32_16x16x32_bf16 v[166:169], v[92:95], v[166:169], 0
	s_add_i32 s8, s26, s43
	s_mulk_i32 s40, 0x4100
	s_waitcnt lgkmcnt(6)
	v_mfma_f32_16x16x32_bf16 v[92:95], v[92:95], v[170:173], 0
	s_waitcnt vmcnt(20) lgkmcnt(5)
	v_mfma_f32_16x16x32_bf16 v[166:169], v[96:99], v[174:177], v[166:169]
	s_waitcnt lgkmcnt(4)
	v_mfma_f32_16x16x32_bf16 v[92:95], v[96:99], v[178:181], v[92:95]
	s_waitcnt vmcnt(19) lgkmcnt(3)
	v_mfma_f32_16x16x32_bf16 v[96:99], v[88:91], v[182:185], v[166:169]
	s_waitcnt lgkmcnt(2)
	v_mfma_f32_16x16x32_bf16 v[88:91], v[88:91], v[186:189], v[92:95]
	s_nop 1
	v_lshl_add_u32 v166, v156, 2, s8
	s_mov_b32 s8, 0xe800
	v_add3_u32 v166, v166, v154, s8
	s_waitcnt vmcnt(18) lgkmcnt(1)
	v_mfma_f32_16x16x32_bf16 v[96:99], v[84:87], v[190:193], v[96:99]
	s_waitcnt lgkmcnt(0)
	v_mfma_f32_16x16x32_bf16 v[84:87], v[84:87], v[194:197], v[88:91]
	s_nop 5
	v_mul_f32_e32 v96, 0x3db504f3, v96
	s_nop 0
	v_mul_f32_e32 v84, 0x3db504f3, v84
	v_mul_f32_e32 v92, 0x3db504f3, v97
	ds_write2_b32 v166, v96, v84 offset1:16
	v_mul_f32_e32 v84, 0x3db504f3, v85
	v_mul_f32_e32 v93, 0x3db504f3, v98
	ds_write2_b32 v166, v92, v84 offset0:65 offset1:81
	v_mul_f32_e32 v84, 0x3db504f3, v86
	v_mul_f32_e32 v94, 0x3db504f3, v99
	ds_write2_b32 v166, v93, v84 offset0:130 offset1:146
	v_mul_f32_e32 v84, 0x3db504f3, v87
	ds_write2_b32 v166, v94, v84 offset0:195 offset1:211
	v_add_u32_e32 v84, s40, v160
	v_add_u32_e32 v84, 0xe800, v84
	ds_read2_b32 v[92:93], v84 offset1:1
	ds_read2_b32 v[90:91], v84 offset0:2 offset1:3
	ds_read2_b32 v[88:89], v84 offset0:4 offset1:5
	ds_read2_b32 v[86:87], v84 offset0:6 offset1:7
	s_waitcnt lgkmcnt(3)
	v_pk_mul_f32 v[84:85], v[92:93], v[92:93]
	s_waitcnt lgkmcnt(2)
	v_pk_mul_f32 v[94:95], v[90:91], v[90:91]
	v_add_f32_e32 v84, v84, v85
	v_add_f32_e32 v84, v84, v94
	s_waitcnt lgkmcnt(1)
	v_pk_mul_f32 v[96:97], v[88:89], v[88:89]
	v_add_f32_e32 v84, v84, v95
	v_add_f32_e32 v84, v84, v96
	s_waitcnt lgkmcnt(0)
	v_pk_mul_f32 v[98:99], v[86:87], v[86:87]
	v_add_f32_e32 v84, v84, v97
	v_add_f32_e32 v84, v84, v98
	v_add_f32_e32 v84, v84, v99
	s_nop 1
	v_add_f32_dpp v84, v84, v84 quad_perm:[1,0,3,2] row_mask:0xf bank_mask:0xf bound_ctrl:1
	s_nop 1
	v_add_f32_dpp v84, v84, v84 quad_perm:[2,3,0,1] row_mask:0xf bank_mask:0xf bound_ctrl:1
	s_nop 1
	v_mov_b32_dpp v85, v84 row_half_mirror row_mask:0xf bank_mask:0xf bound_ctrl:1
	s_and_saveexec_b64 s[8:9], s[4:5]
	s_cbranch_execz .LBB0_1090
	v_add_f32_e32 v94, v84, v85
	s_nop 1
	s_add_u32 s44, s6, 0x1a901000
	s_addc_u32 s45, s7, 0
	global_store_dword v120, v94, s[44:45]
.LBB0_1090:
	s_or_b64 exec, exec, s[8:9]
	s_waitcnt vmcnt(17)
	v_lshlrev_b32_e32 v96, 16, v36
	v_and_b32_e32 v97, 0xffff0000, v36
	v_mul_f32_e32 v36, 0xbfb8aa3b, v96
	v_exp_f32_e32 v36, v36
	v_pk_mul_f32 v[92:93], v[20:21], v[92:93]
	v_pk_mul_f32 v[90:91], v[22:23], v[90:91]
	v_pk_mul_f32 v[88:89], v[16:17], v[88:89]
	v_add_f32_e32 v36, 1.0, v36
	v_rcp_f32_e32 v98, v36
	v_mul_f32_e32 v36, 0xbfb8aa3b, v97
	v_exp_f32_e32 v36, v36
	s_mov_b64 s[8:9], 0x40000
	v_pk_mul_f32 v[86:87], v[18:19], v[86:87]
	v_lshl_add_u64 v[84:85], v[138:139], 0, s[8:9]
	v_add_f32_e32 v36, 1.0, v36
	v_rcp_f32_e32 v99, v36
	s_mov_b32 s8, 0x12840000
	s_mulk_i32 s39, 0x6c00
	s_mov_b64 s[40:41], 0x4000
	v_pk_mul_f32 v[96:97], v[98:99], v[96:97]
	v_lshl_add_u64 v[94:95], v[142:143], 0, s[40:41]
	v_pk_mul_f32 v[92:93], v[96:97], v[92:93]
	v_lshl_add_u64 v[138:139], v[140:141], 0, s[40:41]
	v_cvt_pk_bf16_f32 v36, v92, v93
	v_lshlrev_b32_e32 v92, 16, v37
	v_and_b32_e32 v93, 0xffff0000, v37
	v_mul_f32_e32 v37, 0xbfb8aa3b, v92
	v_exp_f32_e32 v37, v37
	s_nop 0
	v_add_f32_e32 v37, 1.0, v37
	v_rcp_f32_e32 v96, v37
	v_mul_f32_e32 v37, 0xbfb8aa3b, v93
	v_exp_f32_e32 v37, v37
	s_nop 0
	v_add_f32_e32 v37, 1.0, v37
	v_rcp_f32_e32 v97, v37
	s_nop 0
	v_pk_mul_f32 v[92:93], v[96:97], v[92:93]
	s_nop 0
	v_pk_mul_f32 v[90:91], v[92:93], v[90:91]
	s_nop 0
	v_cvt_pk_bf16_f32 v37, v90, v91
	v_lshlrev_b32_e32 v90, 16, v38
	v_and_b32_e32 v91, 0xffff0000, v38
	v_mul_f32_e32 v38, 0xbfb8aa3b, v90
	v_exp_f32_e32 v38, v38
	s_nop 0
	v_add_f32_e32 v38, 1.0, v38
	v_rcp_f32_e32 v92, v38
	v_mul_f32_e32 v38, 0xbfb8aa3b, v91
	v_exp_f32_e32 v38, v38
	s_nop 0
	v_add_f32_e32 v38, 1.0, v38
	v_rcp_f32_e32 v93, v38
	s_nop 0
	v_pk_mul_f32 v[90:91], v[92:93], v[90:91]
	s_nop 0
	v_pk_mul_f32 v[88:89], v[90:91], v[88:89]
	s_nop 0
	v_cvt_pk_bf16_f32 v38, v88, v89
	v_lshlrev_b32_e32 v88, 16, v39
	v_and_b32_e32 v89, 0xffff0000, v39
	v_mul_f32_e32 v39, 0xbfb8aa3b, v88
	v_exp_f32_e32 v39, v39
	s_nop 0
	v_add_f32_e32 v39, 1.0, v39
	v_rcp_f32_e32 v90, v39
	v_mul_f32_e32 v39, 0xbfb8aa3b, v89
	v_exp_f32_e32 v39, v39
	s_nop 0
	v_add_f32_e32 v39, 1.0, v39
	v_rcp_f32_e32 v91, v39
	s_nop 0
	v_pk_mul_f32 v[88:89], v[90:91], v[88:89]
	s_nop 0
	v_pk_mul_f32 v[86:87], v[88:89], v[86:87]
	s_nop 0
	v_cvt_pk_bf16_f32 v39, v86, v87
	s_mov_b32 s8, 0x40000
	s_nop 0
	s_add_u32 s44, s6, 0x12840000
	s_addc_u32 s45, s7, 0
	global_store_dwordx4 v122, v[36:39], s[44:45]
	s_waitcnt lgkmcnt(0)
	s_barrier
	s_nop 0
	v_add_u32_e32 v36, s39, v148
	ds_write_b128 v36, v[56:59]
	ds_write_b128 v36, v[60:63] offset:9216
	ds_write_b128 v36, v[64:67] offset:18432
	s_nop 1
	s_add_u32 s44, s6, 0x8000
	s_addc_u32 s45, s7, 0
	global_load_dwordx4 v[56:59], v124, s[44:45]
	s_nop 1
	s_add_u32 s44, s6, 0xa000
	s_addc_u32 s45, s7, 0
	global_load_dwordx4 v[60:63], v124, s[44:45]
	s_mov_b32 s8, 0xb414000
	s_nop 0
	s_add_u32 s44, s6, 0x80000
	s_addc_u32 s45, s7, 0
	global_load_dwordx4 v[64:67], v126, s[44:45]
	s_nop 1
	s_add_u32 s44, s6, 0xb414000
	s_addc_u32 s45, s7, 0
	global_load_dwordx4 v[92:95], v128, s[44:45]
	global_load_dwordx4 v[96:99], v128, s[44:45] offset:64
	global_load_dwordx4 v[88:91], v128, s[44:45] offset:128
	global_load_dwordx4 v[84:87], v128, s[44:45] offset:192
	s_nop 1
	s_add_u32 s44, s6, 0x8000
	s_addc_u32 s45, s7, 0
	global_load_dwordx4 v[36:39], v130, s[44:45]
	ds_read_b128 v[136:139], v161 offset:1024
	ds_read_b128 v[140:143], v161 offset:1056
	ds_read_b128 v[166:169], v161 offset:1088
	ds_read_b128 v[170:173], v161 offset:1120
	s_waitcnt lgkmcnt(3)
	v_pk_mul_f32 v[0:1], v[0:1], v[136:137]
	v_mov_b32_e32 v136, s38
	s_waitcnt lgkmcnt(1)
	v_pk_mul_f32 v[10:11], v[10:11], v[168:169]
	s_waitcnt lgkmcnt(0)
	v_pk_mul_f32 v[14:15], v[14:15], v[172:173]
	v_pk_mul_f32 v[6:7], v[6:7], v[142:143]
	v_pk_mul_f32 v[2:3], v[2:3], v[138:139]
	v_pk_mul_f32 v[12:13], v[12:13], v[170:171]
	v_pk_mul_f32 v[8:9], v[8:9], v[166:167]
	v_pk_mul_f32 v[4:5], v[4:5], v[140:141]
	s_nop 0
	v_add_u32_e32 v182, v136, v147
	v_add_u32_e32 v186, v136, v145
	ds_read_b128 v[136:139], v182
	ds_read_b128 v[140:143], v182 offset:32
	ds_read_b128 v[166:169], v186 offset:18432
	ds_read_b128 v[170:173], v186 offset:18464
	ds_read_b128 v[174:177], v182 offset:64
	ds_read_b128 v[178:181], v186 offset:18496
	ds_read_b128 v[182:185], v182 offset:96
	ds_read_b128 v[186:189], v186 offset:18528
	s_waitcnt lgkmcnt(5)
	v_mfma_f32_32x32x16_bf16 v[0:15], v[136:139], v[166:169], v[0:15]
	s_waitcnt lgkmcnt(4)
	v_mfma_f32_32x32x16_bf16 v[0:15], v[140:143], v[170:173], v[0:15]
	s_waitcnt lgkmcnt(2)
	v_mfma_f32_32x32x16_bf16 v[0:15], v[174:177], v[178:181], v[0:15]
	s_waitcnt lgkmcnt(0)
	v_mfma_f32_32x32x16_bf16 v[0:15], v[182:185], v[186:189], v[0:15]
	s_nop 11
	v_cvt_pk_bf16_f32 v136, v0, v1
	v_cvt_pk_bf16_f32 v137, v2, v3
	v_cvt_pk_bf16_f32 v138, v4, v5
	v_cvt_pk_bf16_f32 v139, v6, v7
	ds_write2_b64 v162, v[136:137], v[138:139] offset1:2
	v_cvt_pk_bf16_f32 v136, v8, v9
	v_cvt_pk_bf16_f32 v137, v10, v11
	v_cvt_pk_bf16_f32 v138, v12, v13
	v_cvt_pk_bf16_f32 v139, v14, v15
	ds_write2_b64 v162, v[136:137], v[138:139] offset0:4 offset1:6
	ds_read_b128 v[136:139], v164
	ds_read_b128 v[140:143], v164 offset:4352
	ds_read_b128 v[166:169], v164 offset:64
	ds_read_b128 v[170:173], v164 offset:4416
	ds_read_b128 v[174:177], v164 offset:128
	ds_read_b128 v[178:181], v164 offset:4480
	ds_read_b128 v[182:185], v164 offset:192
	ds_read_b128 v[186:189], v164 offset:4544
	s_waitcnt vmcnt(23) lgkmcnt(7)
	v_mfma_f32_16x16x32_bf16 v[136:139], v[116:119], v[136:139], 0
	s_waitcnt lgkmcnt(6)
	v_mfma_f32_16x16x32_bf16 v[116:119], v[116:119], v[140:143], 0
	s_waitcnt vmcnt(22) lgkmcnt(5)
	v_mfma_f32_16x16x32_bf16 v[136:139], v[112:115], v[166:169], v[136:139]
	s_waitcnt lgkmcnt(4)
	v_mfma_f32_16x16x32_bf16 v[112:115], v[112:115], v[170:173], v[116:119]
	s_waitcnt vmcnt(21) lgkmcnt(3)
	v_mfma_f32_16x16x32_bf16 v[116:119], v[108:111], v[174:177], v[136:139]
	s_waitcnt lgkmcnt(2)
	v_mfma_f32_16x16x32_bf16 v[108:111], v[108:111], v[178:181], v[112:115]
	s_waitcnt vmcnt(20) lgkmcnt(1)
	v_mfma_f32_16x16x32_bf16 v[116:119], v[104:107], v[182:185], v[116:119]
	s_waitcnt lgkmcnt(0)
	v_mfma_f32_16x16x32_bf16 v[104:107], v[104:107], v[186:189], v[108:111]
	s_nop 5
	v_mul_f32_e32 v116, 0x3db504f3, v116
	s_nop 0
	v_mul_f32_e32 v104, 0x3db504f3, v104
	v_mul_f32_e32 v112, 0x3db504f3, v117
	ds_write2_b32 v163, v116, v104 offset1:16
	v_mul_f32_e32 v104, 0x3db504f3, v105
	v_mul_f32_e32 v113, 0x3db504f3, v118
	ds_write2_b32 v163, v112, v104 offset0:65 offset1:81
	v_mul_f32_e32 v104, 0x3db504f3, v106
	v_mul_f32_e32 v114, 0x3db504f3, v119
	ds_write2_b32 v163, v113, v104 offset0:130 offset1:146
	v_mul_f32_e32 v104, 0x3db504f3, v107
	ds_write2_b32 v163, v114, v104 offset0:195 offset1:211
	ds_read2_b32 v[110:111], v165 offset1:1
	ds_read2_b32 v[108:109], v165 offset0:2 offset1:3
	ds_read2_b32 v[106:107], v165 offset0:4 offset1:5
	ds_read2_b32 v[104:105], v165 offset0:6 offset1:7
	s_waitcnt lgkmcnt(3)
	v_pk_mul_f32 v[112:113], v[110:111], v[110:111]
	s_waitcnt lgkmcnt(2)
	v_pk_mul_f32 v[114:115], v[108:109], v[108:109]
	v_add_f32_e32 v112, v112, v113
	v_add_f32_e32 v112, v112, v114
	s_waitcnt lgkmcnt(1)
	v_pk_mul_f32 v[116:117], v[106:107], v[106:107]
	v_add_f32_e32 v112, v112, v115
	v_add_f32_e32 v112, v112, v116
	s_waitcnt lgkmcnt(0)
	v_pk_mul_f32 v[118:119], v[104:105], v[104:105]
	v_add_f32_e32 v112, v112, v117
	v_add_f32_e32 v112, v112, v118
	v_add_f32_e32 v112, v112, v119
	s_nop 1
	v_add_f32_dpp v112, v112, v112 quad_perm:[1,0,3,2] row_mask:0xf bank_mask:0xf bound_ctrl:1
	s_nop 1
	v_add_f32_dpp v112, v112, v112 quad_perm:[2,3,0,1] row_mask:0xf bank_mask:0xf bound_ctrl:1
	s_nop 1
	v_mov_b32_dpp v113, v112 row_half_mirror row_mask:0xf bank_mask:0xf bound_ctrl:1
	s_and_saveexec_b64 s[8:9], s[4:5]
	s_cbranch_execz .LBB0_1085
	v_add_f32_e32 v114, v112, v113
	s_nop 1
	s_add_u32 s44, s6, 0x1a902000
	s_addc_u32 s45, s7, 0
	global_store_dword v120, v114, s[44:45]
	s_branch .LBB0_1085
